# rwkv_apply state-owning waves run at raised priority (s_setprio 2, back to 0 after the loop)
# speedup vs baseline: 1.0100x; 1.0100x over previous
.LBB0_1020:
	s_and_b64 vcc, exec, s[0:1]
	s_cbranch_vccz .LBB0_1045
	s_ashr_i32 s4, s2, 4
	s_lshl_b32 s0, s2, 6
	s_ashr_i32 s5, s4, 31
	s_and_b32 s3, s0, 0x3c0
	s_cmpk_lt_u32 s33, 0x100
	s_mov_b64 s[0:1], -1
	s_cbranch_scc0 .LBB0_1025
	s_lshl_b32 s17, s57, 4
	v_or_b32_e32 v0, s3, v133
	v_or_b32_e32 v0, s17, v0
	v_mov_b32_e32 v2, 0
	v_lshlrev_b32_e32 v0, 2, v0
	v_mov_b32_e32 v1, v2
	v_lshl_add_u64 v[0:1], s[40:41], 0, v[0:1]
	v_add_co_u32_e32 v0, vcc, 0x2000, v0
	s_and_b32 s18, s2, 15
	s_nop 0
	v_addc_co_u32_e32 v1, vcc, 0, v1, vcc
	global_load_dword v76, v[0:1], off
	s_lshr_b32 s19, s33, 1
	s_lshl_b64 s[0:1], s[4:5], 23
	s_lshl_b32 s18, s18, 7
	s_and_b32 s19, s19, 0x7fffffe0
	s_add_u32 s18, s19, s18
	s_addc_u32 s19, 0, 0
	v_lshlrev_b32_e32 v0, 5, v146
	v_and_b32_e32 v1, 48, v144
	s_add_u32 s0, s18, s0
	s_waitcnt vmcnt(12)
	v_and_b32_e32 v85, 0x600, v0
	v_lshlrev_b32_e32 v0, 9, v1
	v_mov_b32_e32 v1, v2
	s_addc_u32 s1, s19, s1
	s_waitcnt lgkmcnt(0)
	s_barrier
	v_lshl_add_u64 v[0:1], s[0:1], 0, v[0:1]
	v_lshl_or_b32 v0, v133, 1, v0
	s_mov_b32 s8, 0
	s_waitcnt vmcnt(1)
	v_lshlrev_b32_e32 v82, 4, v146
	v_lshlrev_b32_e32 v83, 3, v146
	v_cmp_gt_u32_e32 vcc, 16, v146
	s_mov_b64 s[6:7], 0
	v_lshlrev_b32_e32 v84, 1, v133
	s_movk_i32 s5, 0x7fff
	s_brev_b32 s9, 16
	s_mov_b32 s10, 0x8001000
	s_mov_b32 s11, 0x8008000
	s_mov_b32 s12, 0x8009000
	s_mov_b32 s13, 0x8010000
	s_mov_b32 s14, 0x8011000
	s_mov_b32 s15, 0x8018000
	s_mov_b32 s16, 0x8019000
	v_mov_b32_e32 v44, v2
	v_mov_b32_e32 v45, v2
	v_mov_b32_e32 v46, v2
	v_mov_b32_e32 v47, v2
	v_mov_b32_e32 v48, v2
	v_mov_b32_e32 v49, v2
	v_mov_b32_e32 v50, v2
	v_mov_b32_e32 v51, v2
	v_mov_b32_e32 v28, v2
	v_mov_b32_e32 v29, v2
	v_mov_b32_e32 v30, v2
	v_mov_b32_e32 v31, v2
	v_mov_b32_e32 v36, v2
	v_mov_b32_e32 v37, v2
	v_mov_b32_e32 v38, v2
	s_lshl_b32 s17, s17, 1
	v_lshl_add_u64 v[78:79], s[52:53], 0, v[0:1]
	v_mov_b32_e32 v39, v2
	s_waitcnt vmcnt(0)
	v_mov_b32_e32 v77, v76
	s_setprio 2
	v_lshlrev_b32_e32 v150, 4, v146
	v_lshlrev_b32_e32 v151, 3, v146
	v_lshrrev_b32_e32 v216, 4, v146
	v_and_b32_e32 v217, 15, v146
	s_lshl_b32 s12, s57, 5
	v_lshlrev_b32_e32 v152, 9, v216
	v_lshl_add_u32 v152, v217, 1, v152
	v_add_u32_e32 v152, s12, v152
	s_lshr_b32 s12, s2, 4
	s_lshl_b32 s12, s12, 22
	s_and_b32 s13, s2, 15
	s_lshl_b32 s13, s13, 6
	s_add_u32 s12, s12, s13
	s_lshl_b32 s13, s57, 4
	s_add_u32 s12, s12, s13
	v_lshl_add_u32 v153, v216, 12, v217
	v_add_u32_e32 v153, s12, v153
	v_lshlrev_b32_e32 v153, 1, v153
	s_add_u32 s6, s52, 0x8000000
	s_addc_u32 s7, s53, 0
	v_mov_b32_e32 v46, 0
	v_mov_b32_e32 v47, 0
	v_mov_b32_e32 v50, 0
	v_mov_b32_e32 v51, 0
	v_mov_b32_e32 v54, 0
	v_mov_b32_e32 v55, 0
	v_mov_b32_e32 v58, 0
	v_mov_b32_e32 v59, 0
	v_mov_b32_e32 v62, 0
	v_mov_b32_e32 v63, 0
	v_mov_b32_e32 v64, 0
	v_mov_b32_e32 v65, 0
	v_mov_b32_e32 v66, 0
	v_mov_b32_e32 v67, 0
	v_mov_b32_e32 v68, 0
	v_mov_b32_e32 v122, 0
	v_mov_b32_e32 v123, 0
	v_mov_b32_e32 v126, 0
	v_mov_b32_e32 v127, 0
	v_mov_b32_e32 v130, 0
	v_mov_b32_e32 v131, 0
	v_mov_b32_e32 v142, 0
	v_mov_b32_e32 v143, 0
	v_mov_b32_e32 v158, 0
	v_mov_b32_e32 v159, 0
	v_mov_b32_e32 v160, 0
	v_mov_b32_e32 v161, 0
	v_mov_b32_e32 v162, 0
	v_mov_b32_e32 v163, 0
	v_mov_b32_e32 v164, 0
	v_mov_b32_e32 v214, 0
	v_mov_b32_e32 v215, 0
	v_mov_b32_e32 v204, 0
	v_mov_b32_e32 v205, 0
	v_mov_b32_e32 v206, 0
	v_mov_b32_e32 v207, 0
	v_mov_b32_e32 v208, 0
	v_mov_b32_e32 v209, 0
	v_mov_b32_e32 v210, 0
	v_mov_b32_e32 v211, 0
	s_mov_b32 s4, 0
	s_lshr_b32 s5, s4, 1
	s_and_b32 s5, s5, 3
	s_mul_i32 s5, s5, 29952
	s_and_b32 s12, s4, 1
	s_mul_i32 s12, s12, 14976
	s_add_u32 s5, s5, s12
	v_add_u32_e32 v149, s5, v152
	v_add_u32_e32 v148, s5, v151
	v_add_u32_e32 v147, s5, v150
	ds_read_u16_d16_hi v64, v149 offset:12800
	ds_read_u16_d16_hi v65, v149 offset:12928
	ds_read_u16_d16_hi v66, v149 offset:13056
	ds_read_u16_d16_hi v67, v149 offset:13184
	ds_read_u16_d16_hi v68, v149 offset:13312
	ds_read_b64 v[60:61], v148 offset:12288
	ds_read_b64 v[44:45], v148 offset:8192
	ds_read_b64 v[48:49], v148 offset:8704
	ds_read_b64 v[52:53], v148 offset:9216
	ds_read_b64 v[56:57], v148 offset:9728
	ds_read_b128 v[36:39], v147 offset:10240
	ds_read_b128 v[40:43], v147 offset:11264
	ds_read_b128 v[4:7], v147 offset:0
	ds_read_b128 v[8:11], v147 offset:1024
	ds_read_b128 v[12:15], v147 offset:2048
	ds_read_b128 v[16:19], v147 offset:3072
	ds_read_b128 v[20:23], v147 offset:4096
	ds_read_b128 v[24:27], v147 offset:5120
	ds_read_b128 v[28:31], v147 offset:6144
	ds_read_b128 v[32:35], v147 offset:7168
	s_waitcnt lgkmcnt(0)
	s_mov_b64 exec, 0xffff
	v_mov_b32_e32 v64, 0
	s_mov_b64 exec, -1
	v_sub_f32_e32 v216, v64, v65
	v_sub_f32_e32 v217, v65, v66
	v_sub_f32_e32 v218, v66, v67
	v_sub_f32_e32 v219, v67, v68
	v_fma_f32 v216, v76, v216, v65
	v_fma_f32 v217, v76, v217, v66
	v_fma_f32 v218, v76, v218, v67
	v_fma_f32 v219, v76, v219, v68
	v_cvt_pk_bf16_f32 v212, v216, v217
	v_cvt_pk_bf16_f32 v213, v218, v219
	s_nop 1
	v_mfma_f32_16x16x32_bf16 v[200:203], v[60:63], v[212:215], 0
	v_mfma_f32_16x16x32_bf16 v[168:171], v[44:47], v[212:215], 0
	v_mfma_f32_16x16x32_bf16 v[172:175], v[48:51], v[212:215], 0
	v_mfma_f32_16x16x32_bf16 v[176:179], v[52:55], v[212:215], 0
	v_mfma_f32_16x16x32_bf16 v[180:183], v[56:59], v[212:215], 0

.Lapc_done:
	s_setprio 0
	s_mov_b64 s[0:1], 0
